# speedup vs baseline: 1.0102x; 1.0000x over previous
; #define QK_FENCE() __builtin_amdgcn_sched_barrier(0x406)
; DI void finishSM(f32x16& p0, f32x16& p1, float alpha, float& l_reg, bf16x8& pa0, bf16x8& pa1, bf16x8& pa2, bf16x8& pa3) {
; #pragma unroll
;   for (int r = 0; r < 16; ++r) p1[r] = __builtin_amdgcn_exp2f(p1[r]);
;   float ps = 0;
; #pragma unroll
;   for (int r = 0; r < 16; ++r) ps += p0[r];
; #pragma unroll
;   for (int r = 0; r < 16; ++r) ps += p1[r];
;   { auto rr = __builtin_amdgcn_permlane32_swap(__float_as_uint(ps), __float_as_uint(ps), false, false);
;     ps = __uint_as_float(rr[0]) + __uint_as_float(rr[1]); }
;   l_reg = l_reg * alpha + ps;
; DI void qkt12(f32x16& p0, f32x16& p1, const char* Kt, const char* Rt, const int* ko, const int* ro, const bf16x8* qr) {
;   { const f32x16 z = {0.f, 0.f, 0.f, 0.f, 0.f, 0.f, 0.f, 0.f, 0.f, 0.f, 0.f, 0.f, 0.f, 0.f, 0.f, 0.f}; p0 = z; p1 = z; }
;   const char* kp[4] = {Kt + ko[0], Kt + ko[1], Kt + ko[2], Kt + ko[3]};
;   const char* rp[4] = {Rt + ro[0], Rt + ro[1], Rt + ro[2], Rt + ro[3]};
;   bf16x8 ka[2], kb[2];
;   ka[0] = *reinterpret_cast<const bf16x8*>(kp[0]); kb[0] = *reinterpret_cast<const bf16x8*>(kp[0] + 8192);
; #pragma unroll
;   for (int d0 = 0; d0 < 12; ++d0) {
;     if (d0 + 1 < 12) { const int d1 = d0 + 1;
;       if (d1 < 8) { ka[d1 & 1] = *reinterpret_cast<const bf16x8*>(kp[d1 & 3] + (d1 >> 2) * 128); kb[d1 & 1] = *reinterpret_cast<const bf16x8*>(kp[d1 & 3] + (d1 >> 2) * 128 + 8192); }
;       else { ka[d1 & 1] = *reinterpret_cast<const bf16x8*>(rp[d1 - 8]); kb[d1 & 1] = *reinterpret_cast<const bf16x8*>(rp[d1 - 8] + 4096); } }
;     QK_FENCE();
;     p0 = __builtin_amdgcn_mfma_f32_32x32x16_bf16(ka[d0 & 1], qr[d0], p0, 0, 0, 0);
;     p1 = __builtin_amdgcn_mfma_f32_32x32x16_bf16(kb[d0 & 1], qr[d0], p1, 0, 0, 0);
;     QK_FENCE();
;   }
.LBB0_122:
	v_sub_co_u32_e64 v64, s[6:7], s61, 1
	s_and_b64 s[6:7], s[6:7], exec
	v_readfirstlane_b32 s2, v64
	s_cselect_b32 s13, 2, s2
	s_mul_i32 s42, s61, 0xa000
	s_add_i32 s45, s42, 16
	v_add_u32_e32 v177, s45, v176
	ds_read_b128 v[64:67], v177 offset:16384
	v_add_u32_e32 v220, s45, v179
	ds_read_b128 v[68:71], v177 offset:24576
	ds_read_b128 v[188:191], v220 offset:16384
	ds_read_b128 v[208:211], v220 offset:24576
	v_add_u32_e32 v221, s45, v180
	v_add_u32_e32 v222, s45, v181
	v_exp_f32_e32 v200, v200
	v_exp_f32_e32 v202, v202
	v_exp_f32_e32 v201, v201
	v_exp_f32_e32 v204, v204
	v_exp_f32_e32 v203, v203
	v_exp_f32_e32 v206, v206
	v_exp_f32_e32 v205, v205
	v_exp_f32_e32 v207, v207
	v_exp_f32_e32 v192, v192
	v_exp_f32_e32 v194, v194
	v_exp_f32_e32 v193, v193
	v_exp_f32_e32 v196, v196
	v_exp_f32_e32 v195, v195
	v_exp_f32_e32 v198, v198
	v_exp_f32_e32 v197, v197
	v_exp_f32_e32 v199, v199
	v_exp_f32_e32 v166, v166
	s_waitcnt lgkmcnt(3)
	v_mfma_f32_32x32x16_bf16 v[80:95], v[64:67], v[134:137], 0
	v_exp_f32_e32 v167, v167
	v_exp_f32_e32 v163, v163
	v_exp_f32_e32 v168, v168
	v_mfma_f32_32x32x16_bf16 v[64:79], v[68:71], v[134:137], 0
	ds_read_b128 v[212:215], v221 offset:16384
	ds_read_b128 v[216:219], v221 offset:24576
	v_exp_f32_e32 v169, v169
	v_exp_f32_e32 v235, v162
	v_exp_f32_e32 v237, v164
	s_waitcnt lgkmcnt(2)
	v_mfma_f32_32x32x16_bf16 v[64:79], v[208:211], v[130:133], v[64:79]
	s_add_i32 s2, s42, 0xa000
	s_cmp_lg_u32 s61, 2
	s_cselect_b32 s2, s2, 0
	v_add_u32_e32 v240, s2, v178
	s_add_u32 s0, s82, 0x1bbc0100
	s_addc_u32 s1, s83, 0
	v_lshl_add_u64 v[238:239], v[150:151], 0, s[0:1]
	v_readfirstlane_b32 s2, v240
	s_mov_b32 m0, s2
	v_exp_f32_e32 v241, v165
	global_load_lds_dwordx4 v[238:239], off
	v_mfma_f32_32x32x16_bf16 v[80:95], v[188:191], v[130:133], v[80:95]
	ds_read_b128 v[188:191], v222 offset:16384
	ds_read_b128 v[208:211], v222 offset:24576
	v_exp_f32_e32 v243, v158
	v_exp_f32_e32 v244, v159
	v_exp_f32_e32 v245, v154
	s_waitcnt lgkmcnt(2)
	v_mfma_f32_32x32x16_bf16 v[64:79], v[216:219], v[126:129], v[64:79]
	v_add_f32_e32 v154, 0, v200
	v_add_f32_e32 v154, v202, v154
	v_add_f32_e32 v154, v201, v154
	v_add_f32_e32 v154, v204, v154
	v_add_f32_e32 v154, v203, v154
	v_add_f32_e32 v154, v206, v154
	v_mfma_f32_32x32x16_bf16 v[80:95], v[212:215], v[126:129], v[80:95]
	ds_read_b128 v[212:215], v177 offset:16512
	ds_read_b128 v[216:219], v177 offset:24704
	v_add_u32_e32 v177, s45, v182
	v_add_f32_e32 v154, v205, v154
	v_add_f32_e32 v154, v207, v154
	v_add_f32_e32 v154, v192, v154
	v_add_f32_e32 v154, v194, v154
	v_add_f32_e32 v154, v193, v154
	s_waitcnt lgkmcnt(2)
	v_mfma_f32_32x32x16_bf16 v[64:79], v[208:211], v[114:117], v[64:79]
	v_add_u32_e32 v242, 0x2000, v240
	s_add_u32 s0, s82, 0x1bbe0100
	s_addc_u32 s1, s83, 0
	v_lshl_add_u64 v[238:239], v[150:151], 0, s[0:1]
	v_readfirstlane_b32 s2, v242
	s_mov_b32 m0, s2
	v_add_f32_e32 v154, v196, v154
	global_load_lds_dwordx4 v[238:239], off
	v_add_f32_e32 v154, v195, v154
	v_add_f32_e32 v154, v198, v154
	v_mfma_f32_32x32x16_bf16 v[80:95], v[188:191], v[114:117], v[80:95]
	ds_read_b128 v[188:191], v220 offset:16512
	ds_read_b128 v[208:211], v220 offset:24704
	v_add_f32_e32 v154, v197, v154
	v_add_f32_e32 v154, v199, v154
	v_exp_f32_e32 v246, v160
	v_add_f32_e32 v154, v166, v154
	s_waitcnt lgkmcnt(2)
	v_mfma_f32_32x32x16_bf16 v[64:79], v[216:219], v[110:113], v[64:79]
	v_exp_f32_e32 v248, v161
	v_add_f32_e32 v154, v167, v154
	v_exp_f32_e32 v249, v156
	v_add_f32_e32 v154, v235, v154
	v_mfma_f32_32x32x16_bf16 v[80:95], v[212:215], v[110:113], v[80:95]
	ds_read_b128 v[212:215], v221 offset:16512
	ds_read_b128 v[216:219], v221 offset:24704
	v_exp_f32_e32 v250, v157
	v_add_f32_e32 v154, v163, v154
	v_add_f32_e32 v154, v246, v154
	v_exp_f32_e32 v251, v155
	s_waitcnt lgkmcnt(2)
	v_mfma_f32_32x32x16_bf16 v[64:79], v[208:211], v[106:109], v[64:79]
	v_add_u32_e32 v242, 0x4000, v240
	s_add_u32 s0, s82, 0x1bbc0000
	s_addc_u32 s1, s83, 0
	v_lshl_add_u64 v[238:239], v[152:153], 0, s[0:1]
	v_readfirstlane_b32 s2, v242
	s_mov_b32 m0, s2
	v_add_f32_e32 v154, v248, v154
	global_load_lds_dwordx4 v[238:239], off
	v_add_f32_e32 v154, v249, v154
	v_add_f32_e32 v154, v250, v154
	v_mfma_f32_32x32x16_bf16 v[80:95], v[188:191], v[106:109], v[80:95]
	ds_read_b128 v[188:191], v222 offset:16512
	ds_read_b128 v[208:211], v222 offset:24704
	v_add_f32_e32 v154, v245, v154
	v_add_f32_e32 v154, v251, v154
	v_add_f32_e32 v154, v168, v154
	v_add_f32_e32 v154, v169, v154
	v_add_f32_e32 v154, v237, v154
	v_add_f32_e32 v154, v241, v154
	s_waitcnt lgkmcnt(2)
	v_mfma_f32_32x32x16_bf16 v[64:79], v[216:219], v[102:105], v[64:79]
	v_add_f32_e32 v154, v243, v154
	v_cvt_pk_bf16_f32 v155, v201, v204
	v_cvt_pk_bf16_f32 v156, v203, v206
	v_cvt_pk_bf16_f32 v157, v205, v207
	v_cvt_pk_bf16_f32 v158, v192, v194
	v_cvt_pk_bf16_f32 v159, v193, v196
	v_mfma_f32_32x32x16_bf16 v[80:95], v[212:215], v[102:105], v[80:95]
	ds_read_b128 v[212:215], v177 offset:32768
	ds_read_b128 v[216:219], v177 offset:36864
	v_add_u32_e32 v177, s45, v183
	v_cvt_pk_bf16_f32 v160, v195, v198
	v_cvt_pk_bf16_f32 v161, v197, v199
	v_permlane32_swap_b32_e32 v155, v157
	v_permlane32_swap_b32_e32 v158, v160
	v_permlane32_swap_b32_e32 v159, v161
	s_waitcnt lgkmcnt(2)
	v_mfma_f32_32x32x16_bf16 v[64:79], v[208:211], v[98:101], v[64:79]
	v_add_u32_e32 v242, 0x6000, v240
	s_add_u32 s0, s82, 0x1bbe0000
	s_addc_u32 s1, s83, 0
	v_lshl_add_u64 v[238:239], v[152:153], 0, s[0:1]
	v_readfirstlane_b32 s2, v242
	s_mov_b32 m0, s2
	v_cvt_pk_bf16_f32 v162, v166, v167
	global_load_lds_dwordx4 v[238:239], off
	v_cvt_pk_bf16_f32 v163, v235, v163
	v_cvt_pk_bf16_f32 v164, v246, v248
	v_mfma_f32_32x32x16_bf16 v[80:95], v[188:191], v[98:101], v[80:95]
	ds_read_b128 v[188:191], v177 offset:32768
	ds_read_b128 v[208:211], v177 offset:36864
	v_add_u32_e32 v177, s45, v184
	v_cvt_pk_bf16_f32 v165, v249, v250
	v_cvt_pk_bf16_f32 v166, v245, v251
	v_cvt_pk_bf16_f32 v167, v168, v169
	v_cvt_pk_bf16_f32 v168, v237, v241
	v_cvt_pk_bf16_f32 v169, v243, v244
	s_waitcnt lgkmcnt(2)
; DI void finishSM(f32x16& p0, f32x16& p1, float alpha, float& l_reg, bf16x8& pa0, bf16x8& pa1, bf16x8& pa2, bf16x8& pa3) {
; #pragma unroll
;   for (int r = 0; r < 16; ++r) p1[r] = __builtin_amdgcn_exp2f(p1[r]);
;   float ps = 0;
; #pragma unroll
;   for (int r = 0; r < 16; ++r) ps += p0[r];
; #pragma unroll
;   for (int r = 0; r < 16; ++r) ps += p1[r];
;   { auto rr = __builtin_amdgcn_permlane32_swap(__float_as_uint(ps), __float_as_uint(ps), false, false);
;     ps = __uint_as_float(rr[0]) + __uint_as_float(rr[1]); }
;   l_reg = l_reg * alpha + ps;
;     ...
;   PK4(p0, 0, pa0); PK4(p0, 8, pa1); PK4(p1, 0, pa2); PK4(p1, 8, pa3);
;     ...
; }
; DI void qkt(f32x16& p0, f32x16& p1, const char* Ks, const char* Rs, const bf16x8* qr, const char* qrl, int r32, int hi) {
;   { const f32x16 z = {0.f, 0.f, 0.f, 0.f, 0.f, 0.f, 0.f, 0.f, 0.f, 0.f, 0.f, 0.f, 0.f, 0.f, 0.f, 0.f}; p0 = z; p1 = z; }
; #pragma unroll
;   for (int d0 = 0; d0 < 8; ++d0) { const int cb = (d0 * 16 + hi * 8) * 2;
;     bf16x8 b0 = *reinterpret_cast<const bf16x8*>(Ks + KSWZ(r32, cb));
;     bf16x8 b1 = *reinterpret_cast<const bf16x8*>(Ks + KSWZ(32 + r32, cb));
;     p0 = __builtin_amdgcn_mfma_f32_32x32x16_bf16(b0, qr[d0], p0, 0, 0, 0);
;     p1 = __builtin_amdgcn_mfma_f32_32x32x16_bf16(b1, qr[d0], p1, 0, 0, 0); }
; #pragma unroll
;   for (int d0 = 0; d0 < 4; ++d0) { const int cb = (d0 * 16 + hi * 8) * 2;
;     bf16x8 b0 = *reinterpret_cast<const bf16x8*>(Rs + RSWZ(r32, cb));
;     bf16x8 b1 = *reinterpret_cast<const bf16x8*>(Rs + RSWZ(32 + r32, cb));
;     const bf16x8 qv = *reinterpret_cast<const bf16x8*>(qrl + d0 * 1024);
;     p0 = __builtin_amdgcn_mfma_f32_32x32x16_bf16(b0, qv, p0, 0, 0, 0);
;     p1 = __builtin_amdgcn_mfma_f32_32x32x16_bf16(b1, qv, p1, 0, 0, 0); }
; }
; DI int v_st(int k, int c) { const int kk = (k & ~0xC) | ((k & 4) << 1) | ((k & 8) >> 1); return ((kk >> 3) * 4 + (c >> 5)) * 512 + ((kk & 7) * 32 + (c & 31)) * 2; }
; DI int v_rd_base(int lane) { return ((lane & 3) << 3) | (((lane >> 2) & 3) << 6) | (((lane >> 4) & 1) << 5) | (((lane >> 5) & 1) << 8); }
; template <int OFF> DI s16x4 tr_read(int vb) { s16x4 r; asm volatile("ds_read_b64_tr_b16 %0, %1 offset:%2" : "=&v"(r) : "v"(vb), "i"(OFF) : "memory"); return r; }
; template <int D0> DI void pv_one(f32x16& od, int vb, bf16x8 pa0, bf16x8 pa1, bf16x8 pa2, bf16x8 pa3) {
	v_mfma_f32_32x32x16_bf16 v[64:79], v[216:219], v[122:125], v[64:79]
	v_permlane32_swap_b32_e32 v162, v164
	v_permlane32_swap_b32_e32 v163, v165
	v_permlane32_swap_b32_e32 v166, v168
	v_permlane32_swap_b32_e32 v167, v169
	v_max_f32_e32 v241, v187, v187
	v_mfma_f32_32x32x16_bf16 v[80:95], v[212:215], v[122:125], v[80:95]
	ds_read_b128 v[212:215], v177 offset:32768
	ds_read_b128 v[216:219], v177 offset:36864
	v_add_u32_e32 v177, s45, v185
	s_waitcnt lgkmcnt(2)
	v_mfma_f32_32x32x16_bf16 v[64:79], v[208:211], v[142:145], v[64:79]
	v_add_u32_e32 v242, 0x8000, v240
	s_add_u32 s0, s82, 0x1fb44000
	s_addc_u32 s1, s83, 0
	v_lshl_add_u64 v[238:239], v[148:149], 0, s[0:1]
	v_readfirstlane_b32 s2, v242
	s_mov_b32 m0, s2
	s_nop 0
	global_load_lds_dwordx4 v[238:239], off
	s_movk_i32 s0, 0x410
	s_movk_i32 s1, 0x1800
	v_mfma_f32_32x32x16_bf16 v[80:95], v[188:191], v[142:145], v[80:95]
	ds_read_b128 v[188:191], v177 offset:32768
	ds_read_b128 v[208:211], v177 offset:36864
	s_waitcnt lgkmcnt(2)
	v_mfma_f32_32x32x16_bf16 v[64:79], v[216:219], v[118:121], v[64:79]
	v_mfma_f32_32x32x16_bf16 v[80:95], v[212:215], v[118:121], v[80:95]
	s_waitcnt lgkmcnt(0)
	v_mfma_f32_32x32x16_bf16 v[64:79], v[208:211], v[138:141], v[64:79]
	v_mfma_f32_32x32x16_bf16 v[80:95], v[188:191], v[138:141], v[80:95]
	s_mul_i32 s44, s13, 0xa000
	v_add_u32_e32 v177, s44, v174
	ds_read_b64_tr_b16 v[190:191], v177 offset:0
	ds_read_b64_tr_b16 v[192:193], v177 offset:0x800
	ds_read_b64_tr_b16 v[194:195], v177 offset:0x1000
	ds_read_b64_tr_b16 v[196:197], v177 offset:0x1800
	ds_read_b64_tr_b16 v[198:199], v177 offset:0x2000
	v_add_f32_e32 v188, v244, v154
	v_mov_b32_e32 v189, v188
	v_cvt_pk_bf16_f32 v154, v200, v202
	ds_read_b64_tr_b16 v[200:201], v177 offset:0x2800
	ds_read_b64_tr_b16 v[202:203], v177 offset:0x3000
	ds_read_b64_tr_b16 v[204:205], v177 offset:0x3800
	v_permlane32_swap_b32_e32 v188, v189
	v_permlane32_swap_b32_e32 v154, v156
	s_waitcnt lgkmcnt(6)
	v_max_f32_e32 v235, v81, v81
	v_mfma_f32_32x32x16_bf16 v[0:15], v[154:157], v[190:193], v[0:15]
	ds_read_b64_tr_b16 v[190:191], v177 offset:0x200
	ds_read_b64_tr_b16 v[192:193], v177 offset:0xa00
	v_max_f32_e32 v237, v80, v80
	v_max_f32_e32 v235, v237, v235
	v_max3_f32 v235, v235, v82, v83
	v_max3_f32 v235, v235, v84, v85
	v_max3_f32 v235, v235, v86, v87
	v_max3_f32 v235, v235, v88, v89
	s_waitcnt lgkmcnt(6)
	v_mfma_f32_32x32x16_bf16 v[0:15], v[158:161], v[194:197], v[0:15]
	ds_read_b64_tr_b16 v[194:195], v177 offset:0x1200
	ds_read_b64_tr_b16 v[196:197], v177 offset:0x1a00
	v_max3_f32 v235, v235, v90, v91
	v_max3_f32 v235, v235, v92, v93
	v_max3_f32 v235, v235, v94, v95
	v_max3_f32 v235, v235, v64, v65
	v_max3_f32 v235, v235, v66, v67
	v_max3_f32 v235, v235, v68, v69
	s_waitcnt lgkmcnt(6)
	v_mfma_f32_32x32x16_bf16 v[0:15], v[162:165], v[198:201], v[0:15]
	ds_read_b64_tr_b16 v[198:199], v177 offset:0x2200
	ds_read_b64_tr_b16 v[200:201], v177 offset:0x2a00
	v_max3_f32 v235, v235, v70, v71
	v_max3_f32 v235, v235, v72, v73
	v_max3_f32 v235, v235, v74, v75
	v_max3_f32 v235, v235, v76, v77
	v_max3_f32 v235, v235, v78, v79
	v_mov_b32_e32 v237, v235
	s_waitcnt lgkmcnt(6)
	v_mfma_f32_32x32x16_bf16 v[0:15], v[166:169], v[202:205], v[0:15]
	ds_read_b64_tr_b16 v[202:203], v177 offset:0x3200
	ds_read_b64_tr_b16 v[204:205], v177 offset:0x3a00
	v_permlane32_swap_b32_e32 v235, v237
	v_max_f32_e32 v237, v237, v237
	v_max_f32_e32 v235, v235, v235
	s_waitcnt lgkmcnt(6)
	v_mfma_f32_32x32x16_bf16 v[48:63], v[154:157], v[190:193], v[48:63]
	ds_read_b64_tr_b16 v[190:191], v177 offset:0x400
	ds_read_b64_tr_b16 v[192:193], v177 offset:0xc00
	s_waitcnt lgkmcnt(6)
	v_mfma_f32_32x32x16_bf16 v[48:63], v[158:161], v[194:197], v[48:63]
	ds_read_b64_tr_b16 v[194:195], v177 offset:0x1400
	ds_read_b64_tr_b16 v[196:197], v177 offset:0x1c00
	s_waitcnt lgkmcnt(6)
	v_mfma_f32_32x32x16_bf16 v[48:63], v[162:165], v[198:201], v[48:63]
	ds_read_b64_tr_b16 v[198:199], v177 offset:0x2400
	ds_read_b64_tr_b16 v[200:201], v177 offset:0x2c00
	s_waitcnt lgkmcnt(6)
	v_mfma_f32_32x32x16_bf16 v[48:63], v[166:169], v[202:205], v[48:63]
	ds_read_b64_tr_b16 v[202:203], v177 offset:0x3400
	ds_read_b64_tr_b16 v[204:205], v177 offset:0x3c00
	s_waitcnt lgkmcnt(6)
	v_mfma_f32_32x32x16_bf16 v[32:47], v[154:157], v[190:193], v[32:47]
	ds_read_b64_tr_b16 v[190:191], v177 offset:0x600
	ds_read_b64_tr_b16 v[192:193], v177 offset:0xe00
	s_waitcnt lgkmcnt(6)
	v_mfma_f32_32x32x16_bf16 v[32:47], v[158:161], v[194:197], v[32:47]
	ds_read_b64_tr_b16 v[194:195], v177 offset:0x1600
	ds_read_b64_tr_b16 v[196:197], v177 offset:0x1e00
	s_waitcnt lgkmcnt(6)
	v_mfma_f32_32x32x16_bf16 v[32:47], v[162:165], v[198:201], v[32:47]
	ds_read_b64_tr_b16 v[198:199], v177 offset:0x2600
	ds_read_b64_tr_b16 v[200:201], v177 offset:0x2e00
	s_waitcnt lgkmcnt(6)
	v_mfma_f32_32x32x16_bf16 v[32:47], v[166:169], v[202:205], v[32:47]
	ds_read_b64_tr_b16 v[202:203], v177 offset:0x3600
	ds_read_b64_tr_b16 v[204:205], v177 offset:0x3e00
	s_waitcnt vmcnt(0)
	s_waitcnt lgkmcnt(0)
	s_barrier
	v_mfma_f32_32x32x16_bf16 v[16:31], v[154:157], v[190:193], v[16:31]
	v_mfma_f32_32x32x16_bf16 v[16:31], v[158:161], v[194:197], v[16:31]
	v_max_f32_e32 v160, v235, v237
	v_sub_f32_e32 v235, v160, v187
	v_max_f32_e32 v160, v241, v160
	v_sub_f32_e32 v241, v187, v160
	v_mul_f32_e32 v241, 0x3dd53b94, v241
	v_mfma_f32_32x32x16_bf16 v[16:31], v[162:165], v[198:201], v[16:31]
	v_exp_f32_e32 v241, v241
	v_mfma_f32_32x32x16_bf16 v[16:31], v[166:169], v[202:205], v[16:31]
	v_cmp_ge_f32_e32 vcc, s65, v235
	s_cmp_eq_u64 vcc, exec
	s_waitcnt vmcnt(0)
	s_cselect_b64 s[38:39], -1, 0
	s_add_i32 s2, s12, -1
	s_cmp_ge_u32 s2, s52
	v_lshl_add_u64 v[158:159], v[150:151], 0, s[82:83]
	v_lshl_add_u64 v[156:157], v[152:153], 0, s[82:83]
	v_lshl_add_u64 v[154:155], v[148:149], 0, s[82:83]
	v_cndmask_b32_e64 v191, v241, 1.0, s[38:39]
	v_cmp_gt_f32_e32 vcc, 1.0, v191
; #define SBAR() __builtin_amdgcn_sched_barrier(0)
; #define RESC(a) do { if (__any((a) < 1.f)) { if (hi == 0) al_l[r32] = (a); asm volatile("s_waitcnt lgkmcnt(0)" ::: "memory"); \
;     _Pragma("unroll") for (int d = 0; d < 4; ++d) _Pragma("unroll") for (int r = 0; r < 16; ++r) o[d][r] *= al_l[crow(r, hi)]; } } while (0)
; #define RESC(a) do { if (__any((a) < 1.f)) { if (hi == 0) al_l[r32] = (a); asm volatile("s_waitcnt lgkmcnt(0)" ::: "memory"); \
;     _Pragma("unroll") for (int d = 0; d < 4; ++d) _Pragma("unroll") for (int r = 0; r < 16; ++r) o[d][r] *= al_l[crow(r, hi)]; } } while (0)
; DI void attn_item_dma(const u16* Qb, const u16* Kh, const u16* Vh, const u16* Rh, u16* Ob, int seq, const float* rope, int pos0, char* lds) {
;     ...
;     if (j + 2 < NT) DMA(j + 2, sp);
;     RESC(alB);
;     SBAR(); qkt12(pA0, pA1, lds + sn * STG + 16384, lds + sn * STG + 32768, ko, ro, qr);
;     finishSM(pB0, pB1, alB, l_reg, pa0, pa1, pa2, pa3); SBAR();
.LBB0_124:
	s_cbranch_vccz .LBB0_128
	s_and_saveexec_b64 s[6:7], s[36:37]
	ds_write_b32 v172, v191 offset:128
	s_or_b64 exec, exec, s[6:7]
	s_waitcnt lgkmcnt(0)
	v_add_u32_e32 v161, v147, v96
	ds_read_b128 v[162:165], v161 offset:224
	ds_read_b128 v[166:169], v161 offset:192
	ds_read_b128 v[192:195], v161 offset:160
	ds_read_b128 v[196:199], v161 offset:128
	s_waitcnt lgkmcnt(0)
	v_pk_mul_f32 v[12:13], v[12:13], v[162:163]
	v_pk_mul_f32 v[8:9], v[8:9], v[166:167]
	v_pk_mul_f32 v[4:5], v[4:5], v[192:193]
	v_pk_mul_f32 v[14:15], v[14:15], v[164:165]
	v_pk_mul_f32 v[10:11], v[10:11], v[168:169]
	v_pk_mul_f32 v[6:7], v[6:7], v[194:195]
	v_pk_mul_f32 v[2:3], v[2:3], v[198:199]
	v_pk_mul_f32 v[0:1], v[0:1], v[196:197]
	v_pk_mul_f32 v[60:61], v[60:61], v[162:163]
	v_pk_mul_f32 v[56:57], v[56:57], v[166:167]
	v_pk_mul_f32 v[52:53], v[52:53], v[192:193]
	v_pk_mul_f32 v[62:63], v[62:63], v[164:165]
	v_pk_mul_f32 v[58:59], v[58:59], v[168:169]
	v_pk_mul_f32 v[54:55], v[54:55], v[194:195]
	v_pk_mul_f32 v[50:51], v[50:51], v[198:199]
	v_pk_mul_f32 v[48:49], v[48:49], v[196:197]
	v_pk_mul_f32 v[44:45], v[44:45], v[162:163]
	v_pk_mul_f32 v[40:41], v[40:41], v[166:167]
	v_pk_mul_f32 v[36:37], v[36:37], v[192:193]
	v_pk_mul_f32 v[46:47], v[46:47], v[164:165]
	v_pk_mul_f32 v[42:43], v[42:43], v[168:169]
	v_pk_mul_f32 v[38:39], v[38:39], v[194:195]
	v_pk_mul_f32 v[34:35], v[34:35], v[198:199]
	v_pk_mul_f32 v[32:33], v[32:33], v[196:197]
	v_pk_mul_f32 v[28:29], v[28:29], v[162:163]
	v_pk_mul_f32 v[24:25], v[24:25], v[166:167]
	v_pk_mul_f32 v[20:21], v[20:21], v[192:193]
	v_pk_mul_f32 v[30:31], v[30:31], v[164:165]
	v_pk_mul_f32 v[26:27], v[26:27], v[168:169]
	v_pk_mul_f32 v[22:23], v[22:23], v[194:195]
	v_pk_mul_f32 v[18:19], v[18:19], v[198:199]
	v_pk_mul_f32 v[16:17], v[16:17], v[196:197]
.LBB0_128:
	s_add_i32 s2, s12, -1
	s_cmp_ge_u32 s2, s52
	s_cbranch_scc1 .Lattn_bb2_nodma
	v_cndmask_b32_e64 v160, v160, v187, s[38:39]
	s_add_i32 s2, s42, 0xa000
	s_cmp_lg_u32 s61, 2
	s_cselect_b32 s2, s2, 0
	s_add_i32 s6, s2, 16
	v_add_u32_e32 v213, s6, v176
	ds_read_b128 v[222:225], v213 offset:16384
	v_add_u32_e32 v230, s6, v179
	ds_read_b128 v[226:229], v213 offset:24576
	ds_read_b128 v[214:217], v230 offset:16384
	ds_read_b128 v[218:221], v230 offset:24576
	v_add_u32_e32 v231, s6, v180
	v_add_u32_e32 v234, s6, v181
	v_mul_f32_e32 v197, 0xbdd53b94, v160
	v_fmamk_f32 v161, v94, 0x3dd53b94, v197
	v_fmamk_f32 v194, v80, 0x3dd53b94, v197
	v_fmamk_f32 v196, v81, 0x3dd53b94, v197
	v_fmamk_f32 v192, v82, 0x3dd53b94, v197
	v_fmamk_f32 v195, v83, 0x3dd53b94, v197
	v_fmamk_f32 v187, v84, 0x3dd53b94, v197
	v_fmamk_f32 v193, v85, 0x3dd53b94, v197
	v_fmamk_f32 v169, v86, 0x3dd53b94, v197
	v_fmamk_f32 v190, v87, 0x3dd53b94, v197
	v_fmamk_f32 v166, v88, 0x3dd53b94, v197
	v_fmamk_f32 v168, v89, 0x3dd53b94, v197
	v_fmamk_f32 v164, v90, 0x3dd53b94, v197
	v_fmamk_f32 v167, v91, 0x3dd53b94, v197
	v_fmamk_f32 v162, v92, 0x3dd53b94, v197
	v_fmamk_f32 v165, v93, 0x3dd53b94, v197
	v_fmamk_f32 v163, v95, 0x3dd53b94, v197
	v_fmamk_f32 v208, v74, 0x3dd53b94, v197
	v_fmamk_f32 v209, v75, 0x3dd53b94, v197
	v_fmamk_f32 v198, v64, 0x3dd53b94, v197
	v_fmamk_f32 v199, v65, 0x3dd53b94, v197
	v_fmamk_f32 v200, v66, 0x3dd53b94, v197
	v_fmamk_f32 v201, v67, 0x3dd53b94, v197
	v_fmamk_f32 v202, v68, 0x3dd53b94, v197
	v_fmamk_f32 v203, v69, 0x3dd53b94, v197
	v_fmamk_f32 v204, v70, 0x3dd53b94, v197
	v_fmamk_f32 v205, v71, 0x3dd53b94, v197
	v_fmamk_f32 v206, v72, 0x3dd53b94, v197
	v_fmamk_f32 v207, v73, 0x3dd53b94, v197
	v_fmamk_f32 v210, v76, 0x3dd53b94, v197
	v_fmamk_f32 v211, v77, 0x3dd53b94, v197
	v_fmamk_f32 v212, v78, 0x3dd53b94, v197
	v_fmac_f32_e32 v197, 0x3dd53b94, v79
	v_exp_f32_e32 v161, v161
	s_waitcnt lgkmcnt(3)
	v_mfma_f32_32x32x16_bf16 v[80:95], v[222:225], v[134:137], 0
	v_exp_f32_e32 v194, v194
	v_exp_f32_e32 v196, v196
	v_exp_f32_e32 v192, v192
	s_waitcnt lgkmcnt(2)
	v_mfma_f32_32x32x16_bf16 v[64:79], v[226:229], v[134:137], 0
	ds_read_b128 v[222:225], v231 offset:16384
	ds_read_b128 v[226:229], v231 offset:24576
	v_exp_f32_e32 v195, v195
	v_exp_f32_e32 v187, v187
	v_exp_f32_e32 v193, v193
	s_waitcnt lgkmcnt(3)
	v_mfma_f32_32x32x16_bf16 v[80:95], v[214:217], v[130:133], v[80:95]
	v_add_u32_e32 v240, s44, v178
	v_exp_f32_e32 v169, v169
	v_readfirstlane_b32 s2, v240
	s_mov_b64 s[0:1], 0x1bc00100
	v_lshl_add_u64 v[238:239], v[158:159], 0, s[0:1]
	s_mov_b32 m0, s2
	v_exp_f32_e32 v190, v190
	global_load_lds_dwordx4 v[238:239], off
	s_waitcnt lgkmcnt(2)
	v_mfma_f32_32x32x16_bf16 v[64:79], v[218:221], v[130:133], v[64:79]
	ds_read_b128 v[214:217], v234 offset:16384
	ds_read_b128 v[218:221], v234 offset:24576
	v_exp_f32_e32 v166, v166
	v_exp_f32_e32 v168, v168
	v_exp_f32_e32 v164, v164
	s_waitcnt lgkmcnt(3)
	v_mfma_f32_32x32x16_bf16 v[80:95], v[222:225], v[126:129], v[80:95]
	v_exp_f32_e32 v167, v167
	v_exp_f32_e32 v162, v162
	v_exp_f32_e32 v165, v165
	s_waitcnt lgkmcnt(2)
	v_mfma_f32_32x32x16_bf16 v[64:79], v[226:229], v[126:129], v[64:79]
	ds_read_b128 v[222:225], v213 offset:16512
	ds_read_b128 v[226:229], v213 offset:24704
	v_add_u32_e32 v213, s6, v182
	v_exp_f32_e32 v163, v163
	v_exp_f32_e32 v198, v198
	s_waitcnt lgkmcnt(3)
	v_mfma_f32_32x32x16_bf16 v[80:95], v[214:217], v[114:117], v[80:95]
	v_add_u32_e32 v242, 0x2000, v240
	s_mov_b64 s[0:1], 0x1bc20100
	v_lshl_add_u64 v[238:239], v[158:159], 0, s[0:1]
	v_readfirstlane_b32 s2, v242
	s_mov_b32 m0, s2
	v_exp_f32_e32 v199, v199
	global_load_lds_dwordx4 v[238:239], off
	s_waitcnt lgkmcnt(2)
	v_mfma_f32_32x32x16_bf16 v[64:79], v[218:221], v[114:117], v[64:79]
	ds_read_b128 v[214:217], v230 offset:16512
	ds_read_b128 v[218:221], v230 offset:24704
	v_exp_f32_e32 v200, v200
	v_exp_f32_e32 v201, v201
	v_exp_f32_e32 v202, v202
	s_waitcnt lgkmcnt(3)
; #define QK_FENCE() __builtin_amdgcn_sched_barrier(0x406)
; DI void finishSM(f32x16& p0, f32x16& p1, float alpha, float& l_reg, bf16x8& pa0, bf16x8& pa1, bf16x8& pa2, bf16x8& pa3) {
; #pragma unroll
;   for (int r = 0; r < 16; ++r) p1[r] = __builtin_amdgcn_exp2f(p1[r]);
;   float ps = 0;
; #pragma unroll
;   for (int r = 0; r < 16; ++r) ps += p0[r];
; #pragma unroll
;   for (int r = 0; r < 16; ++r) ps += p1[r];
;   { auto rr = __builtin_amdgcn_permlane32_swap(__float_as_uint(ps), __float_as_uint(ps), false, false);
;     ps = __uint_as_float(rr[0]) + __uint_as_float(rr[1]); }
;   l_reg = l_reg * alpha + ps;
;     ...
;   PK4(p0, 0, pa0); PK4(p0, 8, pa1); PK4(p1, 0, pa2); PK4(p1, 8, pa3);
; DI void qkt12(f32x16& p0, f32x16& p1, const char* Kt, const char* Rt, const int* ko, const int* ro, const bf16x8* qr) {
;   { const f32x16 z = {0.f, 0.f, 0.f, 0.f, 0.f, 0.f, 0.f, 0.f, 0.f, 0.f, 0.f, 0.f, 0.f, 0.f, 0.f, 0.f}; p0 = z; p1 = z; }
;   const char* kp[4] = {Kt + ko[0], Kt + ko[1], Kt + ko[2], Kt + ko[3]};
;   const char* rp[4] = {Rt + ro[0], Rt + ro[1], Rt + ro[2], Rt + ro[3]};
;   bf16x8 ka[2], kb[2];
;   ka[0] = *reinterpret_cast<const bf16x8*>(kp[0]); kb[0] = *reinterpret_cast<const bf16x8*>(kp[0] + 8192);
; #pragma unroll
;   for (int d0 = 0; d0 < 12; ++d0) {
;     if (d0 + 1 < 12) { const int d1 = d0 + 1;
;       if (d1 < 8) { ka[d1 & 1] = *reinterpret_cast<const bf16x8*>(kp[d1 & 3] + (d1 >> 2) * 128); kb[d1 & 1] = *reinterpret_cast<const bf16x8*>(kp[d1 & 3] + (d1 >> 2) * 128 + 8192); }
;       else { ka[d1 & 1] = *reinterpret_cast<const bf16x8*>(rp[d1 - 8]); kb[d1 & 1] = *reinterpret_cast<const bf16x8*>(rp[d1 - 8] + 4096); } }
;     QK_FENCE();
;     p0 = __builtin_amdgcn_mfma_f32_32x32x16_bf16(ka[d0 & 1], qr[d0], p0, 0, 0, 0);
;     p1 = __builtin_amdgcn_mfma_f32_32x32x16_bf16(kb[d0 & 1], qr[d0], p1, 0, 0, 0);
;     QK_FENCE();
;   }
	v_mfma_f32_32x32x16_bf16 v[80:95], v[222:225], v[110:113], v[80:95]
	v_exp_f32_e32 v203, v203
	v_exp_f32_e32 v204, v204
	v_exp_f32_e32 v205, v205
	s_waitcnt lgkmcnt(2)
	v_mfma_f32_32x32x16_bf16 v[64:79], v[226:229], v[110:113], v[64:79]
	ds_read_b128 v[222:225], v231 offset:16512
	ds_read_b128 v[226:229], v231 offset:24704
	v_exp_f32_e32 v206, v206
	v_exp_f32_e32 v207, v207
	v_exp_f32_e32 v210, v210
	s_waitcnt lgkmcnt(3)
	v_mfma_f32_32x32x16_bf16 v[80:95], v[214:217], v[106:109], v[80:95]
	v_add_u32_e32 v242, 0x4000, v240
	s_mov_b64 s[0:1], 0x1bc00000
	v_lshl_add_u64 v[238:239], v[156:157], 0, s[0:1]
	v_readfirstlane_b32 s2, v242
	s_mov_b32 m0, s2
	v_exp_f32_e32 v211, v211
	global_load_lds_dwordx4 v[238:239], off
	s_waitcnt lgkmcnt(2)
	v_mfma_f32_32x32x16_bf16 v[64:79], v[218:221], v[106:109], v[64:79]
	ds_read_b128 v[214:217], v234 offset:16512
	ds_read_b128 v[218:221], v234 offset:24704
	v_exp_f32_e32 v212, v212
	v_exp_f32_e32 v235, v208
	v_exp_f32_e32 v237, v197
	s_waitcnt lgkmcnt(3)
	v_mfma_f32_32x32x16_bf16 v[80:95], v[222:225], v[102:105], v[80:95]
	v_add_f32_e32 v197, 0, v194
	v_add_f32_e32 v197, v196, v197
	v_add_f32_e32 v197, v192, v197
	v_add_f32_e32 v197, v195, v197
	v_add_f32_e32 v197, v187, v197
	v_add_f32_e32 v197, v193, v197
	s_waitcnt lgkmcnt(2)
	v_mfma_f32_32x32x16_bf16 v[64:79], v[226:229], v[102:105], v[64:79]
	ds_read_b128 v[222:225], v213 offset:32768
	ds_read_b128 v[226:229], v213 offset:36864
	v_add_u32_e32 v213, s6, v183
	v_add_f32_e32 v197, v169, v197
	v_add_f32_e32 v197, v190, v197
	v_add_f32_e32 v197, v166, v197
	v_add_f32_e32 v197, v168, v197
	v_add_f32_e32 v197, v164, v197
	s_waitcnt lgkmcnt(3)
	v_mfma_f32_32x32x16_bf16 v[80:95], v[214:217], v[98:101], v[80:95]
	v_add_u32_e32 v242, 0x6000, v240
	s_mov_b64 s[0:1], 0x1bc20000
	v_lshl_add_u64 v[238:239], v[156:157], 0, s[0:1]
	v_readfirstlane_b32 s2, v242
	s_mov_b32 m0, s2
	v_add_f32_e32 v197, v167, v197
	global_load_lds_dwordx4 v[238:239], off
	v_add_f32_e32 v197, v162, v197
	v_add_f32_e32 v197, v165, v197
	s_waitcnt lgkmcnt(2)
	v_mfma_f32_32x32x16_bf16 v[64:79], v[218:221], v[98:101], v[64:79]
	ds_read_b128 v[214:217], v213 offset:32768
	ds_read_b128 v[218:221], v213 offset:36864
	v_add_u32_e32 v213, s6, v184
	v_add_f32_e32 v197, v161, v197
	v_add_f32_e32 v197, v163, v197
	v_add_f32_e32 v197, v198, v197
	v_add_f32_e32 v197, v199, v197
	v_add_f32_e32 v197, v200, v197
	s_waitcnt lgkmcnt(3)
	v_mfma_f32_32x32x16_bf16 v[80:95], v[222:225], v[122:125], v[80:95]
	v_add_f32_e32 v197, v201, v197
	v_add_f32_e32 v197, v202, v197
	v_add_f32_e32 v197, v203, v197
	v_add_f32_e32 v197, v204, v197
	v_exp_f32_e32 v241, v209
	s_waitcnt lgkmcnt(2)
	v_mfma_f32_32x32x16_bf16 v[64:79], v[226:229], v[122:125], v[64:79]
	ds_read_b128 v[222:225], v213 offset:32768
	ds_read_b128 v[226:229], v213 offset:36864
	v_add_u32_e32 v213, s6, v185
	v_add_f32_e32 v197, v205, v197
	v_add_f32_e32 v197, v206, v197
	v_add_f32_e32 v197, v207, v197
	v_add_f32_e32 v197, v235, v197
	v_add_f32_e32 v197, v241, v197
	s_waitcnt lgkmcnt(3)
	v_mfma_f32_32x32x16_bf16 v[80:95], v[214:217], v[142:145], v[80:95]
	v_add_u32_e32 v242, 0x8000, v240
	s_mov_b64 s[0:1], 0x1fb46000
	v_lshl_add_u64 v[238:239], v[154:155], 0, s[0:1]
	v_readfirstlane_b32 s2, v242
	s_mov_b32 m0, s2
	v_add_f32_e32 v197, v210, v197
	global_load_lds_dwordx4 v[238:239], off
	s_movk_i32 s0, 0x410
	s_movk_i32 s1, 0x1800
	v_add_f32_e32 v197, v211, v197
	v_add_f32_e32 v197, v212, v197
	s_waitcnt lgkmcnt(2)
	v_mfma_f32_32x32x16_bf16 v[64:79], v[218:221], v[142:145], v[64:79]
	ds_read_b128 v[214:217], v213 offset:32768
	ds_read_b128 v[218:221], v213 offset:36864
	v_add_f32_e32 v208, v237, v197
	v_mov_b32_e32 v209, v208
	v_cvt_pk_bf16_f32 v194, v194, v196
	v_cvt_pk_bf16_f32 v195, v192, v195
	v_permlane32_swap_b32_e32 v208, v209
	v_cvt_pk_bf16_f32 v196, v187, v193
	s_waitcnt lgkmcnt(3)
	v_mfma_f32_32x32x16_bf16 v[80:95], v[222:225], v[118:121], v[80:95]
	v_cvt_pk_bf16_f32 v197, v169, v190
	v_cvt_pk_bf16_f32 v166, v166, v168
	v_cvt_pk_bf16_f32 v167, v164, v167
	v_cvt_pk_bf16_f32 v168, v162, v165
	v_cvt_pk_bf16_f32 v169, v161, v163
	v_cvt_pk_bf16_f32 v162, v198, v199
	s_waitcnt lgkmcnt(2)
	v_mfma_f32_32x32x16_bf16 v[64:79], v[226:229], v[118:121], v[64:79]
	v_cvt_pk_bf16_f32 v163, v200, v201
	v_cvt_pk_bf16_f32 v164, v202, v203
	v_cvt_pk_bf16_f32 v165, v204, v205
	v_cvt_pk_bf16_f32 v198, v206, v207
	v_cvt_pk_bf16_f32 v199, v235, v241
	v_cvt_pk_bf16_f32 v200, v210, v211
	s_waitcnt lgkmcnt(1)
	v_mfma_f32_32x32x16_bf16 v[80:95], v[214:217], v[138:141], v[80:95]
	v_cvt_pk_bf16_f32 v201, v212, v237
	v_permlane32_swap_b32_e32 v194, v196
	v_permlane32_swap_b32_e32 v195, v197
	v_permlane32_swap_b32_e32 v166, v168
	v_permlane32_swap_b32_e32 v167, v169
	v_permlane32_swap_b32_e32 v162, v164
	s_waitcnt lgkmcnt(0)
	v_mfma_f32_32x32x16_bf16 v[64:79], v[218:221], v[138:141], v[64:79]
	v_add_u32_e32 v161, s42, v174
	ds_read_b64_tr_b16 v[202:203], v161 offset:0
	ds_read_b64_tr_b16 v[204:205], v161 offset:0x800
	ds_read_b64_tr_b16 v[210:211], v161 offset:0x1000
	ds_read_b64_tr_b16 v[212:213], v161 offset:0x1800
	ds_read_b64_tr_b16 v[214:215], v161 offset:0x2000
	ds_read_b64_tr_b16 v[216:217], v161 offset:0x2800
	ds_read_b64_tr_b16 v[218:219], v161 offset:0x3000
	ds_read_b64_tr_b16 v[220:221], v161 offset:0x3800
	v_permlane32_swap_b32_e32 v163, v165
	v_permlane32_swap_b32_e32 v198, v200
	v_permlane32_swap_b32_e32 v199, v201
	v_max_f32_e32 v235, v81, v81
	v_max_f32_e32 v237, v80, v80
	s_waitcnt lgkmcnt(6)
; #define SBAR() __builtin_amdgcn_sched_barrier(0)
; template <int OFF> DI s16x4 tr_read(int vb) { s16x4 r; asm volatile("ds_read_b64_tr_b16 %0, %1 offset:%2" : "=&v"(r) : "v"(vb), "i"(OFF) : "memory"); return r; }
; DI void partialSM(f32x16& p0, f32x16& p1, float& m_reg, float& mn, float& alpha) {
;   constexpr float C = ATT_SCALE * 1.4426950408889634f;
;   float pmax = p0[0];
; #pragma unroll
;   for (int r = 1; r < 16; ++r) pmax = fmaxf(pmax, p0[r]);
; #pragma unroll
;   for (int r = 0; r < 16; ++r) pmax = fmaxf(pmax, p1[r]);
;   { auto rr = __builtin_amdgcn_permlane32_swap(__float_as_uint(pmax), __float_as_uint(pmax), false, false);
;     pmax = fmaxf(__uint_as_float(rr[0]), __uint_as_float(rr[1])); }
;   if (__builtin_expect(__all(pmax - m_reg <= ATT_THR / ATT_SCALE), 1)) { mn = m_reg; alpha = 1.f; }
;   else { mn = fmaxf(m_reg, pmax); alpha = __builtin_amdgcn_exp2f((m_reg - mn) * C); m_reg = mn; }
; template <int D0> DI void pv_one(f32x16& od, int vb, bf16x8 pa0, bf16x8 pa1, bf16x8 pa2, bf16x8 pa3) {
;   const s16x4 l0 = tr_read<v_rd_off(D0, 0, 0)>(vb), h0 = tr_read<v_rd_off(D0, 0, 1)>(vb), l1 = tr_read<v_rd_off(D0, 1, 0)>(vb), h1 = tr_read<v_rd_off(D0, 1, 1)>(vb);
;   const s16x4 l2 = tr_read<v_rd_off(D0, 2, 0)>(vb), h2 = tr_read<v_rd_off(D0, 2, 1)>(vb), l3 = tr_read<v_rd_off(D0, 3, 0)>(vb), h3 = tr_read<v_rd_off(D0, 3, 1)>(vb);
;   asm volatile("s_waitcnt lgkmcnt(0)" ::: "memory"); SBAR();
;     ...
;   od = __builtin_amdgcn_mfma_f32_32x32x16_bf16(pa0, PK(l0, h0), od, 0, 0, 0);
;   od = __builtin_amdgcn_mfma_f32_32x32x16_bf16(pa1, PK(l1, h1), od, 0, 0, 0);
;   od = __builtin_amdgcn_mfma_f32_32x32x16_bf16(pa2, PK(l2, h2), od, 0, 0, 0);
;   od = __builtin_amdgcn_mfma_f32_32x32x16_bf16(pa3, PK(l3, h3), od, 0, 0, 0);
;     ...
; }
; DI void pv_d0(f32x16* o, int vb, bf16x8 pa0, bf16x8 pa1, bf16x8 pa2, bf16x8 pa3) {
;   pv_one<0>(o[0], vb, pa0, pa1, pa2, pa3); pv_one<1>(o[1], vb, pa0, pa1, pa2, pa3); pv_one<2>(o[2], vb, pa0, pa1, pa2, pa3); pv_one<3>(o[3], vb, pa0, pa1, pa2, pa3);
	v_mfma_f32_32x32x16_bf16 v[0:15], v[194:197], v[202:205], v[0:15]
	ds_read_b64_tr_b16 v[202:203], v161 offset:0x200
	ds_read_b64_tr_b16 v[204:205], v161 offset:0xa00
	v_max_f32_e32 v235, v237, v235
	v_max3_f32 v235, v235, v82, v83
	v_max3_f32 v235, v235, v84, v85
	v_max3_f32 v235, v235, v86, v87
	v_max3_f32 v235, v235, v88, v89
	v_max3_f32 v235, v235, v90, v91
	s_waitcnt lgkmcnt(6)
	v_mfma_f32_32x32x16_bf16 v[0:15], v[166:169], v[210:213], v[0:15]
	ds_read_b64_tr_b16 v[210:211], v161 offset:0x1200
	ds_read_b64_tr_b16 v[212:213], v161 offset:0x1a00
	v_max3_f32 v235, v235, v92, v93
	v_max3_f32 v235, v235, v94, v95
	v_max3_f32 v235, v235, v64, v65
	v_max3_f32 v235, v235, v66, v67
	v_max3_f32 v235, v235, v68, v69
	v_max3_f32 v235, v235, v70, v71
	s_waitcnt lgkmcnt(6)
	v_mfma_f32_32x32x16_bf16 v[0:15], v[162:165], v[214:217], v[0:15]
	ds_read_b64_tr_b16 v[214:215], v161 offset:0x2200
	ds_read_b64_tr_b16 v[216:217], v161 offset:0x2a00
	v_max3_f32 v235, v235, v72, v73
	v_max3_f32 v235, v235, v74, v75
	v_max3_f32 v235, v235, v76, v77
	v_max3_f32 v235, v235, v78, v79
	v_mov_b32_e32 v237, v235
	v_max_f32_e32 v154, v160, v160
	s_waitcnt lgkmcnt(6)
	v_mfma_f32_32x32x16_bf16 v[0:15], v[198:201], v[218:221], v[0:15]
	ds_read_b64_tr_b16 v[218:219], v161 offset:0x3200
	ds_read_b64_tr_b16 v[220:221], v161 offset:0x3a00
	v_permlane32_swap_b32_e32 v235, v237
	v_max_f32_e32 v237, v237, v237
	v_max_f32_e32 v235, v235, v235
	s_waitcnt lgkmcnt(6)
	v_mfma_f32_32x32x16_bf16 v[48:63], v[194:197], v[202:205], v[48:63]
	ds_read_b64_tr_b16 v[202:203], v161 offset:0x400
	ds_read_b64_tr_b16 v[204:205], v161 offset:0xc00
	s_waitcnt lgkmcnt(6)
	v_mfma_f32_32x32x16_bf16 v[48:63], v[166:169], v[210:213], v[48:63]
	ds_read_b64_tr_b16 v[210:211], v161 offset:0x1400
	ds_read_b64_tr_b16 v[212:213], v161 offset:0x1c00
	s_waitcnt lgkmcnt(6)
	v_mfma_f32_32x32x16_bf16 v[48:63], v[162:165], v[214:217], v[48:63]
	ds_read_b64_tr_b16 v[214:215], v161 offset:0x2400
	ds_read_b64_tr_b16 v[216:217], v161 offset:0x2c00
	s_waitcnt lgkmcnt(6)
	v_mfma_f32_32x32x16_bf16 v[48:63], v[198:201], v[218:221], v[48:63]
	ds_read_b64_tr_b16 v[218:219], v161 offset:0x3400
	ds_read_b64_tr_b16 v[220:221], v161 offset:0x3c00
	s_waitcnt lgkmcnt(6)
	v_mfma_f32_32x32x16_bf16 v[32:47], v[194:197], v[202:205], v[32:47]
	ds_read_b64_tr_b16 v[202:203], v161 offset:0x600
	ds_read_b64_tr_b16 v[204:205], v161 offset:0xe00
	s_waitcnt lgkmcnt(6)
	v_mfma_f32_32x32x16_bf16 v[32:47], v[166:169], v[210:213], v[32:47]
	ds_read_b64_tr_b16 v[210:211], v161 offset:0x1600
	ds_read_b64_tr_b16 v[212:213], v161 offset:0x1e00
	s_waitcnt lgkmcnt(6)
	v_mfma_f32_32x32x16_bf16 v[32:47], v[162:165], v[214:217], v[32:47]
	ds_read_b64_tr_b16 v[214:215], v161 offset:0x2600
	ds_read_b64_tr_b16 v[216:217], v161 offset:0x2e00
	s_waitcnt lgkmcnt(6)
	v_mfma_f32_32x32x16_bf16 v[32:47], v[198:201], v[218:221], v[32:47]
	ds_read_b64_tr_b16 v[218:219], v161 offset:0x3600
	ds_read_b64_tr_b16 v[220:221], v161 offset:0x3e00
	v_max_f32_e32 v161, v235, v237
	v_sub_f32_e32 v237, v161, v160
	v_max_f32_e32 v154, v154, v161
	v_sub_f32_e32 v241, v160, v154
	v_mul_f32_e32 v241, 0x3dd53b94, v241
	s_waitcnt vmcnt(0)
	s_waitcnt vmcnt(0)
	s_waitcnt lgkmcnt(0)
	s_barrier
	v_mfma_f32_32x32x16_bf16 v[16:31], v[194:197], v[202:205], v[16:31]
	v_exp_f32_e32 v241, v241
	v_mfma_f32_32x32x16_bf16 v[16:31], v[166:169], v[210:213], v[16:31]
	v_mfma_f32_32x32x16_bf16 v[16:31], v[162:165], v[214:217], v[16:31]
	v_mfma_f32_32x32x16_bf16 v[16:31], v[198:201], v[218:221], v[16:31]
	v_cmp_ge_f32_e32 vcc, s65, v237
	s_cmp_eq_u64 vcc, exec
	s_cselect_b64 s[38:39], -1, 0
	s_cmp_ge_u32 s12, s52
	s_cselect_b64 s[42:43], -1, 0
	v_cndmask_b32_e64 v190, v241, 1.0, s[38:39]
	v_cmp_gt_f32_e32 vcc, 1.0, v190
	s_branch .Lattn_bb2_join
.Lattn_bb2_nodma:
	v_cndmask_b32_e64 v160, v160, v187, s[38:39]
	s_add_i32 s2, s42, 0xa000
	s_cmp_lg_u32 s61, 2
	s_cselect_b32 s2, s2, 0
	s_add_i32 s6, s2, 16
	v_add_u32_e32 v213, s6, v176
	ds_read_b128 v[222:225], v213 offset:16384
	v_add_u32_e32 v230, s6, v179
	ds_read_b128 v[226:229], v213 offset:24576
	ds_read_b128 v[214:217], v230 offset:16384
	ds_read_b128 v[218:221], v230 offset:24576
	v_add_u32_e32 v231, s6, v180
	v_add_u32_e32 v234, s6, v181
	v_mul_f32_e32 v197, 0xbdd53b94, v160
	v_fmamk_f32 v161, v94, 0x3dd53b94, v197
	v_fmamk_f32 v194, v80, 0x3dd53b94, v197
	v_fmamk_f32 v196, v81, 0x3dd53b94, v197
	v_fmamk_f32 v192, v82, 0x3dd53b94, v197
	v_fmamk_f32 v195, v83, 0x3dd53b94, v197
	v_fmamk_f32 v187, v84, 0x3dd53b94, v197
	v_fmamk_f32 v193, v85, 0x3dd53b94, v197
	v_fmamk_f32 v169, v86, 0x3dd53b94, v197
	v_fmamk_f32 v190, v87, 0x3dd53b94, v197
	v_fmamk_f32 v166, v88, 0x3dd53b94, v197
	v_fmamk_f32 v168, v89, 0x3dd53b94, v197
	v_fmamk_f32 v164, v90, 0x3dd53b94, v197
	v_fmamk_f32 v167, v91, 0x3dd53b94, v197
	v_fmamk_f32 v162, v92, 0x3dd53b94, v197
	v_fmamk_f32 v165, v93, 0x3dd53b94, v197
	v_fmamk_f32 v163, v95, 0x3dd53b94, v197
	v_fmamk_f32 v208, v74, 0x3dd53b94, v197
	v_fmamk_f32 v209, v75, 0x3dd53b94, v197
	v_fmamk_f32 v198, v64, 0x3dd53b94, v197
	v_fmamk_f32 v199, v65, 0x3dd53b94, v197
	v_fmamk_f32 v200, v66, 0x3dd53b94, v197
	v_fmamk_f32 v201, v67, 0x3dd53b94, v197
	v_fmamk_f32 v202, v68, 0x3dd53b94, v197
	v_fmamk_f32 v203, v69, 0x3dd53b94, v197
	v_fmamk_f32 v204, v70, 0x3dd53b94, v197
	v_fmamk_f32 v205, v71, 0x3dd53b94, v197
	v_fmamk_f32 v206, v72, 0x3dd53b94, v197
	v_fmamk_f32 v207, v73, 0x3dd53b94, v197
	v_fmamk_f32 v210, v76, 0x3dd53b94, v197
	v_fmamk_f32 v211, v77, 0x3dd53b94, v197
	v_fmamk_f32 v212, v78, 0x3dd53b94, v197
	v_fmac_f32_e32 v197, 0x3dd53b94, v79
	v_exp_f32_e32 v161, v161
	s_waitcnt lgkmcnt(3)
; #define QK_FENCE() __builtin_amdgcn_sched_barrier(0x406)
; DI void finishSM(f32x16& p0, f32x16& p1, float alpha, float& l_reg, bf16x8& pa0, bf16x8& pa1, bf16x8& pa2, bf16x8& pa3) {
; #pragma unroll
;   for (int r = 0; r < 16; ++r) p1[r] = __builtin_amdgcn_exp2f(p1[r]);
;   float ps = 0;
; #pragma unroll
;   for (int r = 0; r < 16; ++r) ps += p0[r];
; #pragma unroll
;   for (int r = 0; r < 16; ++r) ps += p1[r];
;   { auto rr = __builtin_amdgcn_permlane32_swap(__float_as_uint(ps), __float_as_uint(ps), false, false);
;     ps = __uint_as_float(rr[0]) + __uint_as_float(rr[1]); }
;   l_reg = l_reg * alpha + ps;
;     ...
;   PK4(p0, 0, pa0); PK4(p0, 8, pa1); PK4(p1, 0, pa2); PK4(p1, 8, pa3);
; DI void qkt12(f32x16& p0, f32x16& p1, const char* Kt, const char* Rt, const int* ko, const int* ro, const bf16x8* qr) {
;   { const f32x16 z = {0.f, 0.f, 0.f, 0.f, 0.f, 0.f, 0.f, 0.f, 0.f, 0.f, 0.f, 0.f, 0.f, 0.f, 0.f, 0.f}; p0 = z; p1 = z; }
;   const char* kp[4] = {Kt + ko[0], Kt + ko[1], Kt + ko[2], Kt + ko[3]};
;   const char* rp[4] = {Rt + ro[0], Rt + ro[1], Rt + ro[2], Rt + ro[3]};
;   bf16x8 ka[2], kb[2];
;   ka[0] = *reinterpret_cast<const bf16x8*>(kp[0]); kb[0] = *reinterpret_cast<const bf16x8*>(kp[0] + 8192);
; #pragma unroll
;   for (int d0 = 0; d0 < 12; ++d0) {
;     if (d0 + 1 < 12) { const int d1 = d0 + 1;
;       if (d1 < 8) { ka[d1 & 1] = *reinterpret_cast<const bf16x8*>(kp[d1 & 3] + (d1 >> 2) * 128); kb[d1 & 1] = *reinterpret_cast<const bf16x8*>(kp[d1 & 3] + (d1 >> 2) * 128 + 8192); }
;       else { ka[d1 & 1] = *reinterpret_cast<const bf16x8*>(rp[d1 - 8]); kb[d1 & 1] = *reinterpret_cast<const bf16x8*>(rp[d1 - 8] + 4096); } }
;     QK_FENCE();
;     p0 = __builtin_amdgcn_mfma_f32_32x32x16_bf16(ka[d0 & 1], qr[d0], p0, 0, 0, 0);
;     p1 = __builtin_amdgcn_mfma_f32_32x32x16_bf16(kb[d0 & 1], qr[d0], p1, 0, 0, 0);
;     QK_FENCE();
;   }
	v_mfma_f32_32x32x16_bf16 v[80:95], v[222:225], v[134:137], 0
	v_exp_f32_e32 v194, v194
	v_exp_f32_e32 v196, v196
	v_exp_f32_e32 v192, v192
	s_waitcnt lgkmcnt(2)
	v_mfma_f32_32x32x16_bf16 v[64:79], v[226:229], v[134:137], 0
	ds_read_b128 v[222:225], v231 offset:16384
	ds_read_b128 v[226:229], v231 offset:24576
	v_exp_f32_e32 v195, v195
	v_exp_f32_e32 v187, v187
	v_exp_f32_e32 v193, v193
	s_waitcnt lgkmcnt(3)
	v_mfma_f32_32x32x16_bf16 v[80:95], v[214:217], v[130:133], v[80:95]
	v_exp_f32_e32 v169, v169
	v_exp_f32_e32 v190, v190
	v_exp_f32_e32 v166, v166
	s_waitcnt lgkmcnt(2)
	v_mfma_f32_32x32x16_bf16 v[64:79], v[218:221], v[130:133], v[64:79]
	ds_read_b128 v[214:217], v234 offset:16384
	ds_read_b128 v[218:221], v234 offset:24576
	v_exp_f32_e32 v168, v168
	v_exp_f32_e32 v164, v164
	v_exp_f32_e32 v167, v167
	s_waitcnt lgkmcnt(3)
	v_mfma_f32_32x32x16_bf16 v[80:95], v[222:225], v[126:129], v[80:95]
	v_exp_f32_e32 v162, v162
	v_exp_f32_e32 v165, v165
	v_exp_f32_e32 v163, v163
	s_waitcnt lgkmcnt(2)
	v_mfma_f32_32x32x16_bf16 v[64:79], v[226:229], v[126:129], v[64:79]
	ds_read_b128 v[222:225], v213 offset:16512
	ds_read_b128 v[226:229], v213 offset:24704
	v_add_u32_e32 v213, s6, v182
	v_exp_f32_e32 v198, v198
	v_exp_f32_e32 v199, v199
	s_waitcnt lgkmcnt(3)
	v_mfma_f32_32x32x16_bf16 v[80:95], v[214:217], v[114:117], v[80:95]
	v_exp_f32_e32 v200, v200
	v_exp_f32_e32 v201, v201
	v_exp_f32_e32 v202, v202
	s_waitcnt lgkmcnt(2)
	v_mfma_f32_32x32x16_bf16 v[64:79], v[218:221], v[114:117], v[64:79]
	ds_read_b128 v[214:217], v230 offset:16512
	ds_read_b128 v[218:221], v230 offset:24704
	v_exp_f32_e32 v203, v203
	v_exp_f32_e32 v204, v204
	v_exp_f32_e32 v205, v205
	s_waitcnt lgkmcnt(3)
	v_mfma_f32_32x32x16_bf16 v[80:95], v[222:225], v[110:113], v[80:95]
	v_exp_f32_e32 v206, v206
	v_exp_f32_e32 v207, v207
	v_exp_f32_e32 v210, v210
	s_waitcnt lgkmcnt(2)
	v_mfma_f32_32x32x16_bf16 v[64:79], v[226:229], v[110:113], v[64:79]
	ds_read_b128 v[222:225], v231 offset:16512
	ds_read_b128 v[226:229], v231 offset:24704
	v_exp_f32_e32 v211, v211
	v_exp_f32_e32 v212, v212
	v_exp_f32_e32 v235, v208
	s_waitcnt lgkmcnt(3)
	v_mfma_f32_32x32x16_bf16 v[80:95], v[214:217], v[106:109], v[80:95]
	v_exp_f32_e32 v237, v197
	v_add_f32_e32 v197, 0, v194
	v_add_f32_e32 v197, v196, v197
	v_add_f32_e32 v197, v192, v197
	v_add_f32_e32 v197, v195, v197
	s_waitcnt lgkmcnt(2)
	v_mfma_f32_32x32x16_bf16 v[64:79], v[218:221], v[106:109], v[64:79]
	ds_read_b128 v[214:217], v234 offset:16512
	ds_read_b128 v[218:221], v234 offset:24704
	v_add_f32_e32 v197, v187, v197
	v_add_f32_e32 v197, v193, v197
	v_add_f32_e32 v197, v169, v197
	v_add_f32_e32 v197, v190, v197
	v_add_f32_e32 v197, v166, v197
	v_add_f32_e32 v197, v168, v197
	s_waitcnt lgkmcnt(3)
	v_mfma_f32_32x32x16_bf16 v[80:95], v[222:225], v[102:105], v[80:95]
	v_add_f32_e32 v197, v164, v197
	v_add_f32_e32 v197, v167, v197
	v_add_f32_e32 v197, v162, v197
	v_add_f32_e32 v197, v165, v197
	v_add_f32_e32 v197, v161, v197
	v_add_f32_e32 v197, v163, v197
	s_waitcnt lgkmcnt(2)
	v_mfma_f32_32x32x16_bf16 v[64:79], v[226:229], v[102:105], v[64:79]
	ds_read_b128 v[222:225], v213 offset:32768
	ds_read_b128 v[226:229], v213 offset:36864
	v_add_u32_e32 v213, s6, v183
	v_add_f32_e32 v197, v198, v197
	v_add_f32_e32 v197, v199, v197
	v_add_f32_e32 v197, v200, v197
	v_add_f32_e32 v197, v201, v197
	v_add_f32_e32 v197, v202, v197
	s_waitcnt lgkmcnt(3)
	v_mfma_f32_32x32x16_bf16 v[80:95], v[214:217], v[98:101], v[80:95]
	v_add_f32_e32 v197, v203, v197
	v_add_f32_e32 v197, v204, v197
	v_exp_f32_e32 v241, v209
	v_add_f32_e32 v197, v205, v197
	v_add_f32_e32 v197, v206, v197
	s_waitcnt lgkmcnt(2)
	v_mfma_f32_32x32x16_bf16 v[64:79], v[218:221], v[98:101], v[64:79]
	ds_read_b128 v[214:217], v213 offset:32768
	ds_read_b128 v[218:221], v213 offset:36864
	v_add_u32_e32 v213, s6, v184
	v_add_f32_e32 v197, v207, v197
	v_add_f32_e32 v197, v235, v197
	v_add_f32_e32 v197, v241, v197
	v_add_f32_e32 v197, v210, v197
	v_add_f32_e32 v197, v211, v197
	s_waitcnt lgkmcnt(3)
	v_mfma_f32_32x32x16_bf16 v[80:95], v[222:225], v[122:125], v[80:95]
	v_add_f32_e32 v197, v212, v197
	v_add_f32_e32 v208, v237, v197
	v_mov_b32_e32 v209, v208
	v_cvt_pk_bf16_f32 v194, v194, v196
	v_cvt_pk_bf16_f32 v195, v192, v195
	v_permlane32_swap_b32_e32 v208, v209
	s_waitcnt lgkmcnt(2)
	v_mfma_f32_32x32x16_bf16 v[64:79], v[226:229], v[122:125], v[64:79]
	ds_read_b128 v[222:225], v213 offset:32768
	ds_read_b128 v[226:229], v213 offset:36864
	v_add_u32_e32 v213, s6, v185
	v_cvt_pk_bf16_f32 v196, v187, v193
	v_cvt_pk_bf16_f32 v197, v169, v190
	v_cvt_pk_bf16_f32 v166, v166, v168
	v_cvt_pk_bf16_f32 v167, v164, v167
	v_cvt_pk_bf16_f32 v168, v162, v165
	s_waitcnt lgkmcnt(3)
	v_mfma_f32_32x32x16_bf16 v[80:95], v[214:217], v[142:145], v[80:95]
	v_cvt_pk_bf16_f32 v169, v161, v163
	v_cvt_pk_bf16_f32 v162, v198, v199
	v_cvt_pk_bf16_f32 v163, v200, v201
	v_cvt_pk_bf16_f32 v164, v202, v203
	v_cvt_pk_bf16_f32 v165, v204, v205
	v_cvt_pk_bf16_f32 v198, v206, v207
	s_waitcnt lgkmcnt(2)
	v_mfma_f32_32x32x16_bf16 v[64:79], v[218:221], v[142:145], v[64:79]
	ds_read_b128 v[214:217], v213 offset:32768
	ds_read_b128 v[218:221], v213 offset:36864
	v_cvt_pk_bf16_f32 v199, v235, v241
	v_cvt_pk_bf16_f32 v200, v210, v211
	v_cvt_pk_bf16_f32 v201, v212, v237
	v_permlane32_swap_b32_e32 v194, v196
	v_permlane32_swap_b32_e32 v195, v197
	v_permlane32_swap_b32_e32 v166, v168
	s_waitcnt lgkmcnt(3)
	v_mfma_f32_32x32x16_bf16 v[80:95], v[222:225], v[118:121], v[80:95]
	v_permlane32_swap_b32_e32 v167, v169
	v_permlane32_swap_b32_e32 v162, v164
	v_permlane32_swap_b32_e32 v163, v165
	v_permlane32_swap_b32_e32 v198, v200
	v_permlane32_swap_b32_e32 v199, v201
	v_max_f32_e32 v154, v160, v160
	s_waitcnt lgkmcnt(2)
; #define SBAR() __builtin_amdgcn_sched_barrier(0)
; template <int OFF> DI s16x4 tr_read(int vb) { s16x4 r; asm volatile("ds_read_b64_tr_b16 %0, %1 offset:%2" : "=&v"(r) : "v"(vb), "i"(OFF) : "memory"); return r; }
; template <int D0> DI void pv_one(f32x16& od, int vb, bf16x8 pa0, bf16x8 pa1, bf16x8 pa2, bf16x8 pa3) {
;   const s16x4 l0 = tr_read<v_rd_off(D0, 0, 0)>(vb), h0 = tr_read<v_rd_off(D0, 0, 1)>(vb), l1 = tr_read<v_rd_off(D0, 1, 0)>(vb), h1 = tr_read<v_rd_off(D0, 1, 1)>(vb);
;   const s16x4 l2 = tr_read<v_rd_off(D0, 2, 0)>(vb), h2 = tr_read<v_rd_off(D0, 2, 1)>(vb), l3 = tr_read<v_rd_off(D0, 3, 0)>(vb), h3 = tr_read<v_rd_off(D0, 3, 1)>(vb);
;   asm volatile("s_waitcnt lgkmcnt(0)" ::: "memory"); SBAR();
;     ...
;   od = __builtin_amdgcn_mfma_f32_32x32x16_bf16(pa0, PK(l0, h0), od, 0, 0, 0);
;   od = __builtin_amdgcn_mfma_f32_32x32x16_bf16(pa1, PK(l1, h1), od, 0, 0, 0);
;   od = __builtin_amdgcn_mfma_f32_32x32x16_bf16(pa2, PK(l2, h2), od, 0, 0, 0);
;   od = __builtin_amdgcn_mfma_f32_32x32x16_bf16(pa3, PK(l3, h3), od, 0, 0, 0);
;     ...
; }
; DI void pv_d0(f32x16* o, int vb, bf16x8 pa0, bf16x8 pa1, bf16x8 pa2, bf16x8 pa3) {
;   pv_one<0>(o[0], vb, pa0, pa1, pa2, pa3); pv_one<1>(o[1], vb, pa0, pa1, pa2, pa3); pv_one<2>(o[2], vb, pa0, pa1, pa2, pa3); pv_one<3>(o[3], vb, pa0, pa1, pa2, pa3);
	v_mfma_f32_32x32x16_bf16 v[64:79], v[226:229], v[118:121], v[64:79]
	s_waitcnt lgkmcnt(1)
	v_mfma_f32_32x32x16_bf16 v[80:95], v[214:217], v[138:141], v[80:95]
	s_waitcnt lgkmcnt(0)
	v_mfma_f32_32x32x16_bf16 v[64:79], v[218:221], v[138:141], v[64:79]
	v_add_u32_e32 v161, s42, v174
	ds_read_b64_tr_b16 v[202:203], v161 offset:0
	ds_read_b64_tr_b16 v[204:205], v161 offset:0x800
	ds_read_b64_tr_b16 v[210:211], v161 offset:0x1000
	ds_read_b64_tr_b16 v[212:213], v161 offset:0x1800
	ds_read_b64_tr_b16 v[214:215], v161 offset:0x2000
	ds_read_b64_tr_b16 v[216:217], v161 offset:0x2800
	ds_read_b64_tr_b16 v[218:219], v161 offset:0x3000
	ds_read_b64_tr_b16 v[220:221], v161 offset:0x3800
	s_waitcnt lgkmcnt(6)
	v_max_f32_e32 v235, v81, v81
	v_max_f32_e32 v237, v80, v80
	v_max_f32_e32 v235, v237, v235
	v_max3_f32 v235, v235, v82, v83
	v_max3_f32 v235, v235, v84, v85
	v_mfma_f32_32x32x16_bf16 v[0:15], v[194:197], v[202:205], v[0:15]
	ds_read_b64_tr_b16 v[202:203], v161 offset:0x200
	ds_read_b64_tr_b16 v[204:205], v161 offset:0xa00
	v_max3_f32 v235, v235, v86, v87
	v_max3_f32 v235, v235, v88, v89
	v_max3_f32 v235, v235, v90, v91
	v_max3_f32 v235, v235, v92, v93
	v_max3_f32 v235, v235, v94, v95
	v_max3_f32 v235, v235, v64, v65
	s_waitcnt lgkmcnt(6)
	v_mfma_f32_32x32x16_bf16 v[0:15], v[166:169], v[210:213], v[0:15]
	ds_read_b64_tr_b16 v[210:211], v161 offset:0x1200
	ds_read_b64_tr_b16 v[212:213], v161 offset:0x1a00
	v_max3_f32 v235, v235, v66, v67
	v_max3_f32 v235, v235, v68, v69
	v_max3_f32 v235, v235, v70, v71
	v_max3_f32 v235, v235, v72, v73
	v_max3_f32 v235, v235, v74, v75
	v_max3_f32 v235, v235, v76, v77
	s_waitcnt lgkmcnt(6)
	v_mfma_f32_32x32x16_bf16 v[0:15], v[162:165], v[214:217], v[0:15]
	ds_read_b64_tr_b16 v[214:215], v161 offset:0x2200
	ds_read_b64_tr_b16 v[216:217], v161 offset:0x2a00
	v_max3_f32 v235, v235, v78, v79
	v_mov_b32_e32 v237, v235
	s_waitcnt lgkmcnt(6)
	v_mfma_f32_32x32x16_bf16 v[0:15], v[198:201], v[218:221], v[0:15]
	ds_read_b64_tr_b16 v[218:219], v161 offset:0x3200
	ds_read_b64_tr_b16 v[220:221], v161 offset:0x3a00
	v_permlane32_swap_b32_e32 v235, v237
	v_max_f32_e32 v237, v237, v237
	v_max_f32_e32 v235, v235, v235
	s_waitcnt lgkmcnt(6)
	v_mfma_f32_32x32x16_bf16 v[48:63], v[194:197], v[202:205], v[48:63]
	ds_read_b64_tr_b16 v[202:203], v161 offset:0x400
	ds_read_b64_tr_b16 v[204:205], v161 offset:0xc00
	s_waitcnt lgkmcnt(6)
	v_mfma_f32_32x32x16_bf16 v[48:63], v[166:169], v[210:213], v[48:63]
	ds_read_b64_tr_b16 v[210:211], v161 offset:0x1400
	ds_read_b64_tr_b16 v[212:213], v161 offset:0x1c00
	s_waitcnt lgkmcnt(6)
	v_mfma_f32_32x32x16_bf16 v[48:63], v[162:165], v[214:217], v[48:63]
	ds_read_b64_tr_b16 v[214:215], v161 offset:0x2400
	ds_read_b64_tr_b16 v[216:217], v161 offset:0x2c00
	s_waitcnt lgkmcnt(6)
	v_mfma_f32_32x32x16_bf16 v[48:63], v[198:201], v[218:221], v[48:63]
	ds_read_b64_tr_b16 v[218:219], v161 offset:0x3400
	ds_read_b64_tr_b16 v[220:221], v161 offset:0x3c00
	s_waitcnt lgkmcnt(6)
	v_mfma_f32_32x32x16_bf16 v[32:47], v[194:197], v[202:205], v[32:47]
	ds_read_b64_tr_b16 v[202:203], v161 offset:0x600
	ds_read_b64_tr_b16 v[204:205], v161 offset:0xe00
	s_waitcnt lgkmcnt(6)
	v_mfma_f32_32x32x16_bf16 v[32:47], v[166:169], v[210:213], v[32:47]
	ds_read_b64_tr_b16 v[210:211], v161 offset:0x1600
	ds_read_b64_tr_b16 v[212:213], v161 offset:0x1e00
	s_waitcnt lgkmcnt(6)
	v_mfma_f32_32x32x16_bf16 v[32:47], v[162:165], v[214:217], v[32:47]
	ds_read_b64_tr_b16 v[214:215], v161 offset:0x2600
	ds_read_b64_tr_b16 v[216:217], v161 offset:0x2e00
	s_waitcnt lgkmcnt(6)
	v_mfma_f32_32x32x16_bf16 v[32:47], v[198:201], v[218:221], v[32:47]
	ds_read_b64_tr_b16 v[218:219], v161 offset:0x3600
	ds_read_b64_tr_b16 v[220:221], v161 offset:0x3e00
	v_max_f32_e32 v161, v235, v237
	v_sub_f32_e32 v237, v161, v160
	v_max_f32_e32 v154, v154, v161
	v_sub_f32_e32 v241, v160, v154
	v_mul_f32_e32 v241, 0x3dd53b94, v241
	s_waitcnt vmcnt(0)
	s_waitcnt vmcnt(0)
	s_waitcnt lgkmcnt(0)
	s_barrier
	v_mfma_f32_32x32x16_bf16 v[16:31], v[194:197], v[202:205], v[16:31]
	v_exp_f32_e32 v241, v241
	v_mfma_f32_32x32x16_bf16 v[16:31], v[166:169], v[210:213], v[16:31]
	v_mfma_f32_32x32x16_bf16 v[16:31], v[162:165], v[214:217], v[16:31]
	v_mfma_f32_32x32x16_bf16 v[16:31], v[198:201], v[218:221], v[16:31]
	v_cmp_ge_f32_e32 vcc, s65, v237
	s_cmp_eq_u64 vcc, exec
	s_cselect_b64 s[38:39], -1, 0
	s_cmp_ge_u32 s12, s52
	s_cselect_b64 s[42:43], -1, 0
	v_cndmask_b32_e64 v190, v241, 1.0, s[38:39]
	v_cmp_gt_f32_e32 vcc, 1.0, v190
.Lattn_bb2_join:
.LBB0_130:
	s_cbranch_vccz .LBB0_134
	s_and_saveexec_b64 s[6:7], s[36:37]
	ds_write_b32 v172, v190 offset:128
	s_or_b64 exec, exec, s[6:7]
	s_waitcnt lgkmcnt(0)
	v_add_u32_e32 v155, v147, v96
	ds_read_b128 v[156:159], v155 offset:224
	ds_read_b128 v[162:165], v155 offset:192
	ds_read_b128 v[166:169], v155 offset:160
	ds_read_b128 v[192:195], v155 offset:128
	s_waitcnt lgkmcnt(0)
	v_pk_mul_f32 v[12:13], v[12:13], v[156:157]
	v_pk_mul_f32 v[8:9], v[8:9], v[162:163]
	v_pk_mul_f32 v[4:5], v[4:5], v[166:167]
	v_pk_mul_f32 v[14:15], v[14:15], v[158:159]
	v_pk_mul_f32 v[10:11], v[10:11], v[164:165]
	v_pk_mul_f32 v[6:7], v[6:7], v[168:169]
	v_pk_mul_f32 v[2:3], v[2:3], v[194:195]
	v_pk_mul_f32 v[0:1], v[0:1], v[192:193]
	v_pk_mul_f32 v[60:61], v[60:61], v[156:157]
	v_pk_mul_f32 v[56:57], v[56:57], v[162:163]
	v_pk_mul_f32 v[52:53], v[52:53], v[166:167]
	v_pk_mul_f32 v[62:63], v[62:63], v[158:159]
	v_pk_mul_f32 v[58:59], v[58:59], v[164:165]
	v_pk_mul_f32 v[54:55], v[54:55], v[168:169]
	v_pk_mul_f32 v[50:51], v[50:51], v[194:195]
	v_pk_mul_f32 v[48:49], v[48:49], v[192:193]
	v_pk_mul_f32 v[44:45], v[44:45], v[156:157]
	v_pk_mul_f32 v[40:41], v[40:41], v[162:163]
	v_pk_mul_f32 v[36:37], v[36:37], v[166:167]
	v_pk_mul_f32 v[46:47], v[46:47], v[158:159]
	v_pk_mul_f32 v[42:43], v[42:43], v[164:165]
	v_pk_mul_f32 v[38:39], v[38:39], v[168:169]
	v_pk_mul_f32 v[34:35], v[34:35], v[194:195]
	v_pk_mul_f32 v[32:33], v[32:33], v[192:193]
	v_pk_mul_f32 v[28:29], v[28:29], v[156:157]
	v_pk_mul_f32 v[24:25], v[24:25], v[162:163]
	v_pk_mul_f32 v[20:21], v[20:21], v[166:167]
	v_pk_mul_f32 v[30:31], v[30:31], v[158:159]
	v_pk_mul_f32 v[26:27], v[26:27], v[164:165]
	v_pk_mul_f32 v[22:23], v[22:23], v[168:169]
	v_pk_mul_f32 v[18:19], v[18:19], v[194:195]
	v_pk_mul_f32 v[16:17], v[16:17], v[192:193]
